# B2 decode-state items hand-written: DPP reductions, packed f32, next item loads in flight
# speedup vs baseline: 1.0045x; 1.0045x over previous
.LBB0_161:
	v_lshrrev_b32_e32 v60, 5, v78
	v_mul_u32_u24_e32 v61, 0x210, v60
	v_lshl_add_u32 v61, v79, 4, v61
	v_add_u32_e32 v62, 0x10800, v61
	v_add_u32_e32 v63, s22, v60
	v_lshlrev_b32_e32 v98, 10, v63
	v_add_u32_e32 v98, s31, v98
	v_lshl_add_u32 v98, v79, 2, v98
	v_lshlrev_b32_e32 v98, 2, v98
	v_lshlrev_b32_e32 v99, 2, v63
	v_xor_b32_e32 v182, 16, v192
	v_lshlrev_b32_e32 v182, 2, v182
	s_add_u32 s20, s94, 0x2500000
	s_addc_u32 s21, s95, 0
	s_and_b64 vcc, exec, s[44:45]
	s_cbranch_vccz .Lcepi_last
	ds_read_b128 v[12:15], v61 offset:0
	v_mov_b32_e32 v134, v98
	global_load_dwordx4 v[100:103], v134, s[92:93]
	ds_read_b128 v[16:19], v61 offset:8448
	v_add_u32_e32 v135, 0x10000, v98
	global_load_dwordx4 v[104:107], v135, s[92:93]
	ds_read_b128 v[20:23], v61 offset:16896
	v_add_u32_e32 v136, 0x20000, v98
	global_load_dwordx4 v[108:111], v136, s[92:93]
	ds_read_b128 v[24:27], v61 offset:25344
	v_add_u32_e32 v137, 0x30000, v98
	global_load_dwordx4 v[112:115], v137, s[92:93]
	ds_read_b128 v[28:31], v61 offset:33792
	v_add_u32_e32 v138, 0x40000, v98
	global_load_dwordx4 v[116:119], v138, s[92:93]
	ds_read_b128 v[32:35], v61 offset:42240
	v_add_u32_e32 v139, 0x50000, v98
	global_load_dwordx4 v[120:123], v139, s[92:93]
	ds_read_b128 v[36:39], v61 offset:50688
	v_add_u32_e32 v140, 0x60000, v98
	global_load_dwordx4 v[124:127], v140, s[92:93]
	ds_read_b128 v[40:43], v61 offset:59136
	v_add_u32_e32 v141, 0x70000, v98
	global_load_dwordx4 v[128:131], v141, s[92:93]
	s_waitcnt vmcnt(7) lgkmcnt(7)
	v_pk_add_f32 v[100:101], v[100:101], v[12:13]
	v_pk_add_f32 v[102:103], v[102:103], v[14:15]
	global_store_dwordx4 v134, v[100:103], s[92:93]
	v_cvt_pk_bf16_f32 v12, v100, v101
	v_cvt_pk_bf16_f32 v13, v102, v103
	v_lshrrev_b32_e32 v14, 1, v134
	v_pk_mul_f32 v[100:101], v[100:101], v[100:101]
	v_pk_mul_f32 v[102:103], v[102:103], v[102:103]
	global_store_dwordx2 v14, v[12:13], s[20:21]
	v_add_f32_e32 v100, v100, v101
	v_add_f32_e32 v102, v102, v103
	v_add_f32_e32 v142, v100, v102
	s_waitcnt vmcnt(8) lgkmcnt(6)
	v_pk_add_f32 v[104:105], v[104:105], v[16:17]
	v_pk_add_f32 v[106:107], v[106:107], v[18:19]
	global_store_dwordx4 v135, v[104:107], s[92:93]
	v_cvt_pk_bf16_f32 v16, v104, v105
	v_cvt_pk_bf16_f32 v17, v106, v107
	v_lshrrev_b32_e32 v18, 1, v135
	v_pk_mul_f32 v[104:105], v[104:105], v[104:105]
	v_pk_mul_f32 v[106:107], v[106:107], v[106:107]
	global_store_dwordx2 v18, v[16:17], s[20:21]
	v_add_f32_e32 v104, v104, v105
	v_add_f32_e32 v106, v106, v107
	v_add_f32_e32 v143, v104, v106
	s_waitcnt vmcnt(9) lgkmcnt(5)
	v_pk_add_f32 v[108:109], v[108:109], v[20:21]
	v_pk_add_f32 v[110:111], v[110:111], v[22:23]
	global_store_dwordx4 v136, v[108:111], s[92:93]
	v_cvt_pk_bf16_f32 v20, v108, v109
	v_cvt_pk_bf16_f32 v21, v110, v111
	v_lshrrev_b32_e32 v22, 1, v136
	v_pk_mul_f32 v[108:109], v[108:109], v[108:109]
	v_pk_mul_f32 v[110:111], v[110:111], v[110:111]
	global_store_dwordx2 v22, v[20:21], s[20:21]
	v_add_f32_e32 v108, v108, v109
	v_add_f32_e32 v110, v110, v111
	v_add_f32_e32 v144, v108, v110
	s_waitcnt vmcnt(10) lgkmcnt(4)
	v_pk_add_f32 v[112:113], v[112:113], v[24:25]
	v_pk_add_f32 v[114:115], v[114:115], v[26:27]
	global_store_dwordx4 v137, v[112:115], s[92:93]
	v_cvt_pk_bf16_f32 v24, v112, v113
	v_cvt_pk_bf16_f32 v25, v114, v115
	v_lshrrev_b32_e32 v26, 1, v137
	v_pk_mul_f32 v[112:113], v[112:113], v[112:113]
	v_pk_mul_f32 v[114:115], v[114:115], v[114:115]
	global_store_dwordx2 v26, v[24:25], s[20:21]
	v_add_f32_e32 v112, v112, v113
	v_add_f32_e32 v114, v114, v115
	v_add_f32_e32 v145, v112, v114
	s_waitcnt vmcnt(11) lgkmcnt(3)
	v_pk_add_f32 v[116:117], v[116:117], v[28:29]
	v_pk_add_f32 v[118:119], v[118:119], v[30:31]
	global_store_dwordx4 v138, v[116:119], s[92:93]
	v_cvt_pk_bf16_f32 v28, v116, v117
	v_cvt_pk_bf16_f32 v29, v118, v119
	v_lshrrev_b32_e32 v30, 1, v138
	v_pk_mul_f32 v[116:117], v[116:117], v[116:117]
	v_pk_mul_f32 v[118:119], v[118:119], v[118:119]
	global_store_dwordx2 v30, v[28:29], s[20:21]
	v_add_f32_e32 v116, v116, v117
	v_add_f32_e32 v118, v118, v119
	v_add_f32_e32 v146, v116, v118
	s_waitcnt vmcnt(12) lgkmcnt(2)
	v_pk_add_f32 v[120:121], v[120:121], v[32:33]
	v_pk_add_f32 v[122:123], v[122:123], v[34:35]
	global_store_dwordx4 v139, v[120:123], s[92:93]
	v_cvt_pk_bf16_f32 v32, v120, v121
	v_cvt_pk_bf16_f32 v33, v122, v123
	v_lshrrev_b32_e32 v34, 1, v139
	v_pk_mul_f32 v[120:121], v[120:121], v[120:121]
	v_pk_mul_f32 v[122:123], v[122:123], v[122:123]
	global_store_dwordx2 v34, v[32:33], s[20:21]
	v_add_f32_e32 v120, v120, v121
	v_add_f32_e32 v122, v122, v123
	v_add_f32_e32 v147, v120, v122
	s_waitcnt vmcnt(13) lgkmcnt(1)
	v_pk_add_f32 v[124:125], v[124:125], v[36:37]
	v_pk_add_f32 v[126:127], v[126:127], v[38:39]
	global_store_dwordx4 v140, v[124:127], s[92:93]
	v_cvt_pk_bf16_f32 v36, v124, v125
	v_cvt_pk_bf16_f32 v37, v126, v127
	v_lshrrev_b32_e32 v38, 1, v140
	v_pk_mul_f32 v[124:125], v[124:125], v[124:125]
	v_pk_mul_f32 v[126:127], v[126:127], v[126:127]
	global_store_dwordx2 v38, v[36:37], s[20:21]
	v_add_f32_e32 v124, v124, v125
	v_add_f32_e32 v126, v126, v127
	v_add_f32_e32 v148, v124, v126
	s_waitcnt vmcnt(14) lgkmcnt(0)
	v_pk_add_f32 v[128:129], v[128:129], v[40:41]
	v_pk_add_f32 v[130:131], v[130:131], v[42:43]
	global_store_dwordx4 v141, v[128:131], s[92:93]
	v_cvt_pk_bf16_f32 v40, v128, v129
	v_cvt_pk_bf16_f32 v41, v130, v131
	v_lshrrev_b32_e32 v42, 1, v141
	v_pk_mul_f32 v[128:129], v[128:129], v[128:129]
	v_pk_mul_f32 v[130:131], v[130:131], v[130:131]
	global_store_dwordx2 v42, v[40:41], s[20:21]
	v_add_f32_e32 v128, v128, v129
	v_add_f32_e32 v130, v130, v131
	v_add_f32_e32 v149, v128, v130
	v_add_f32_dpp v142, v142, v142 quad_perm:[1,0,3,2] row_mask:0xf bank_mask:0xf bound_ctrl:1
	v_add_f32_dpp v143, v143, v143 quad_perm:[1,0,3,2] row_mask:0xf bank_mask:0xf bound_ctrl:1
	v_add_f32_dpp v144, v144, v144 quad_perm:[1,0,3,2] row_mask:0xf bank_mask:0xf bound_ctrl:1
	v_add_f32_dpp v145, v145, v145 quad_perm:[1,0,3,2] row_mask:0xf bank_mask:0xf bound_ctrl:1
	v_add_f32_dpp v146, v146, v146 quad_perm:[1,0,3,2] row_mask:0xf bank_mask:0xf bound_ctrl:1
	v_add_f32_dpp v147, v147, v147 quad_perm:[1,0,3,2] row_mask:0xf bank_mask:0xf bound_ctrl:1
	v_add_f32_dpp v148, v148, v148 quad_perm:[1,0,3,2] row_mask:0xf bank_mask:0xf bound_ctrl:1
	v_add_f32_dpp v149, v149, v149 quad_perm:[1,0,3,2] row_mask:0xf bank_mask:0xf bound_ctrl:1
	v_add_f32_dpp v142, v142, v142 quad_perm:[2,3,0,1] row_mask:0xf bank_mask:0xf bound_ctrl:1
	v_add_f32_dpp v143, v143, v143 quad_perm:[2,3,0,1] row_mask:0xf bank_mask:0xf bound_ctrl:1
	v_add_f32_dpp v144, v144, v144 quad_perm:[2,3,0,1] row_mask:0xf bank_mask:0xf bound_ctrl:1
	v_add_f32_dpp v145, v145, v145 quad_perm:[2,3,0,1] row_mask:0xf bank_mask:0xf bound_ctrl:1
	v_add_f32_dpp v146, v146, v146 quad_perm:[2,3,0,1] row_mask:0xf bank_mask:0xf bound_ctrl:1
	v_add_f32_dpp v147, v147, v147 quad_perm:[2,3,0,1] row_mask:0xf bank_mask:0xf bound_ctrl:1
	v_add_f32_dpp v148, v148, v148 quad_perm:[2,3,0,1] row_mask:0xf bank_mask:0xf bound_ctrl:1
	v_add_f32_dpp v149, v149, v149 quad_perm:[2,3,0,1] row_mask:0xf bank_mask:0xf bound_ctrl:1
	v_add_f32_dpp v142, v142, v142 row_half_mirror row_mask:0xf bank_mask:0xf bound_ctrl:1
	v_add_f32_dpp v143, v143, v143 row_half_mirror row_mask:0xf bank_mask:0xf bound_ctrl:1
	v_add_f32_dpp v144, v144, v144 row_half_mirror row_mask:0xf bank_mask:0xf bound_ctrl:1
	v_add_f32_dpp v145, v145, v145 row_half_mirror row_mask:0xf bank_mask:0xf bound_ctrl:1
	v_add_f32_dpp v146, v146, v146 row_half_mirror row_mask:0xf bank_mask:0xf bound_ctrl:1
	v_add_f32_dpp v147, v147, v147 row_half_mirror row_mask:0xf bank_mask:0xf bound_ctrl:1
	v_add_f32_dpp v148, v148, v148 row_half_mirror row_mask:0xf bank_mask:0xf bound_ctrl:1
	v_add_f32_dpp v149, v149, v149 row_half_mirror row_mask:0xf bank_mask:0xf bound_ctrl:1
	v_add_f32_dpp v142, v142, v142 row_mirror row_mask:0xf bank_mask:0xf bound_ctrl:1
	v_add_f32_dpp v143, v143, v143 row_mirror row_mask:0xf bank_mask:0xf bound_ctrl:1
	v_add_f32_dpp v144, v144, v144 row_mirror row_mask:0xf bank_mask:0xf bound_ctrl:1
	v_add_f32_dpp v145, v145, v145 row_mirror row_mask:0xf bank_mask:0xf bound_ctrl:1
	v_add_f32_dpp v146, v146, v146 row_mirror row_mask:0xf bank_mask:0xf bound_ctrl:1
	v_add_f32_dpp v147, v147, v147 row_mirror row_mask:0xf bank_mask:0xf bound_ctrl:1
	v_add_f32_dpp v148, v148, v148 row_mirror row_mask:0xf bank_mask:0xf bound_ctrl:1
	v_add_f32_dpp v149, v149, v149 row_mirror row_mask:0xf bank_mask:0xf bound_ctrl:1
	ds_bpermute_b32 v12, v182, v142
	ds_bpermute_b32 v16, v182, v143
	ds_bpermute_b32 v20, v182, v144
	ds_bpermute_b32 v24, v182, v145
	ds_bpermute_b32 v28, v182, v146
	ds_bpermute_b32 v32, v182, v147
	ds_bpermute_b32 v36, v182, v148
	ds_bpermute_b32 v40, v182, v149
	s_waitcnt lgkmcnt(0)
	v_add_f32_e32 v142, v142, v12
	v_add_f32_e32 v143, v143, v16
	v_add_f32_e32 v144, v144, v20
	v_add_f32_e32 v145, v145, v24
	v_add_f32_e32 v146, v146, v28
	v_add_f32_e32 v147, v147, v32
	v_add_f32_e32 v148, v148, v36
	v_add_f32_e32 v149, v149, v40
	v_add_u32_e32 v13, 0x0, v99
	v_add_u32_e32 v17, 0x40, v99
	v_add_u32_e32 v21, 0x80, v99
	v_add_u32_e32 v25, 0xc0, v99
	v_add_u32_e32 v29, 0x100, v99
	v_add_u32_e32 v33, 0x140, v99
	v_add_u32_e32 v37, 0x180, v99
	v_add_u32_e32 v41, 0x1c0, v99
	s_mov_b64 exec, s[0:1]
	global_atomic_add_f32 v13, v142, s[50:51]
	global_atomic_add_f32 v17, v143, s[50:51]
	global_atomic_add_f32 v21, v144, s[50:51]
	global_atomic_add_f32 v25, v145, s[50:51]
	global_atomic_add_f32 v29, v146, s[50:51]
	global_atomic_add_f32 v33, v147, s[50:51]
	global_atomic_add_f32 v37, v148, s[50:51]
	global_atomic_add_f32 v41, v149, s[50:51]
	s_mov_b64 exec, -1
	ds_read_b128 v[12:15], v62 offset:0
	v_add_u32_e32 v134, 0x80000, v98
	global_load_dwordx4 v[100:103], v134, s[92:93]
	ds_read_b128 v[16:19], v62 offset:8448
	v_add_u32_e32 v135, 0x90000, v98
	global_load_dwordx4 v[104:107], v135, s[92:93]
	ds_read_b128 v[20:23], v62 offset:16896
	v_add_u32_e32 v136, 0xa0000, v98
	global_load_dwordx4 v[108:111], v136, s[92:93]
	ds_read_b128 v[24:27], v62 offset:25344
	v_add_u32_e32 v137, 0xb0000, v98
	global_load_dwordx4 v[112:115], v137, s[92:93]
	ds_read_b128 v[28:31], v62 offset:33792
	v_add_u32_e32 v138, 0xc0000, v98
	global_load_dwordx4 v[116:119], v138, s[92:93]
	ds_read_b128 v[32:35], v62 offset:42240
	v_add_u32_e32 v139, 0xd0000, v98
	global_load_dwordx4 v[120:123], v139, s[92:93]
	ds_read_b128 v[36:39], v62 offset:50688
	v_add_u32_e32 v140, 0xe0000, v98
	global_load_dwordx4 v[124:127], v140, s[92:93]
	ds_read_b128 v[40:43], v62 offset:59136
	v_add_u32_e32 v141, 0xf0000, v98
	global_load_dwordx4 v[128:131], v141, s[92:93]
	s_waitcnt vmcnt(7) lgkmcnt(7)
	v_pk_add_f32 v[100:101], v[100:101], v[12:13]
	v_pk_add_f32 v[102:103], v[102:103], v[14:15]
	global_store_dwordx4 v134, v[100:103], s[92:93]
	v_cvt_pk_bf16_f32 v12, v100, v101
	v_cvt_pk_bf16_f32 v13, v102, v103
	v_lshrrev_b32_e32 v14, 1, v134
	v_pk_mul_f32 v[100:101], v[100:101], v[100:101]
	v_pk_mul_f32 v[102:103], v[102:103], v[102:103]
	global_store_dwordx2 v14, v[12:13], s[20:21]
	v_add_f32_e32 v100, v100, v101
	v_add_f32_e32 v102, v102, v103
	v_add_f32_e32 v142, v100, v102
	s_waitcnt vmcnt(8) lgkmcnt(6)
	v_pk_add_f32 v[104:105], v[104:105], v[16:17]
	v_pk_add_f32 v[106:107], v[106:107], v[18:19]
	global_store_dwordx4 v135, v[104:107], s[92:93]
	v_cvt_pk_bf16_f32 v16, v104, v105
	v_cvt_pk_bf16_f32 v17, v106, v107
	v_lshrrev_b32_e32 v18, 1, v135
	v_pk_mul_f32 v[104:105], v[104:105], v[104:105]
	v_pk_mul_f32 v[106:107], v[106:107], v[106:107]
	global_store_dwordx2 v18, v[16:17], s[20:21]
	v_add_f32_e32 v104, v104, v105
	v_add_f32_e32 v106, v106, v107
	v_add_f32_e32 v143, v104, v106
	s_waitcnt vmcnt(9) lgkmcnt(5)
	v_pk_add_f32 v[108:109], v[108:109], v[20:21]
	v_pk_add_f32 v[110:111], v[110:111], v[22:23]
	global_store_dwordx4 v136, v[108:111], s[92:93]
	v_cvt_pk_bf16_f32 v20, v108, v109
	v_cvt_pk_bf16_f32 v21, v110, v111
	v_lshrrev_b32_e32 v22, 1, v136
	v_pk_mul_f32 v[108:109], v[108:109], v[108:109]
	v_pk_mul_f32 v[110:111], v[110:111], v[110:111]
	global_store_dwordx2 v22, v[20:21], s[20:21]
	v_add_f32_e32 v108, v108, v109
	v_add_f32_e32 v110, v110, v111
	v_add_f32_e32 v144, v108, v110
	s_waitcnt vmcnt(10) lgkmcnt(4)
	v_pk_add_f32 v[112:113], v[112:113], v[24:25]
	v_pk_add_f32 v[114:115], v[114:115], v[26:27]
	global_store_dwordx4 v137, v[112:115], s[92:93]
	v_cvt_pk_bf16_f32 v24, v112, v113
	v_cvt_pk_bf16_f32 v25, v114, v115
	v_lshrrev_b32_e32 v26, 1, v137
	v_pk_mul_f32 v[112:113], v[112:113], v[112:113]
	v_pk_mul_f32 v[114:115], v[114:115], v[114:115]
	global_store_dwordx2 v26, v[24:25], s[20:21]
	v_add_f32_e32 v112, v112, v113
	v_add_f32_e32 v114, v114, v115
	v_add_f32_e32 v145, v112, v114
	s_waitcnt vmcnt(11) lgkmcnt(3)
	v_pk_add_f32 v[116:117], v[116:117], v[28:29]
	v_pk_add_f32 v[118:119], v[118:119], v[30:31]
	global_store_dwordx4 v138, v[116:119], s[92:93]
	v_cvt_pk_bf16_f32 v28, v116, v117
	v_cvt_pk_bf16_f32 v29, v118, v119
	v_lshrrev_b32_e32 v30, 1, v138
	v_pk_mul_f32 v[116:117], v[116:117], v[116:117]
	v_pk_mul_f32 v[118:119], v[118:119], v[118:119]
	global_store_dwordx2 v30, v[28:29], s[20:21]
	v_add_f32_e32 v116, v116, v117
	v_add_f32_e32 v118, v118, v119
	v_add_f32_e32 v146, v116, v118
	s_waitcnt vmcnt(12) lgkmcnt(2)
	v_pk_add_f32 v[120:121], v[120:121], v[32:33]
	v_pk_add_f32 v[122:123], v[122:123], v[34:35]
	global_store_dwordx4 v139, v[120:123], s[92:93]
	v_cvt_pk_bf16_f32 v32, v120, v121
	v_cvt_pk_bf16_f32 v33, v122, v123
	v_lshrrev_b32_e32 v34, 1, v139
	v_pk_mul_f32 v[120:121], v[120:121], v[120:121]
	v_pk_mul_f32 v[122:123], v[122:123], v[122:123]
	global_store_dwordx2 v34, v[32:33], s[20:21]
	v_add_f32_e32 v120, v120, v121
	v_add_f32_e32 v122, v122, v123
	v_add_f32_e32 v147, v120, v122
	s_waitcnt vmcnt(13) lgkmcnt(1)
	v_pk_add_f32 v[124:125], v[124:125], v[36:37]
	v_pk_add_f32 v[126:127], v[126:127], v[38:39]
	global_store_dwordx4 v140, v[124:127], s[92:93]
	v_cvt_pk_bf16_f32 v36, v124, v125
	v_cvt_pk_bf16_f32 v37, v126, v127
	v_lshrrev_b32_e32 v38, 1, v140
	v_pk_mul_f32 v[124:125], v[124:125], v[124:125]
	v_pk_mul_f32 v[126:127], v[126:127], v[126:127]
	global_store_dwordx2 v38, v[36:37], s[20:21]
	v_add_f32_e32 v124, v124, v125
	v_add_f32_e32 v126, v126, v127
	v_add_f32_e32 v148, v124, v126
	s_waitcnt vmcnt(14) lgkmcnt(0)
	v_pk_add_f32 v[128:129], v[128:129], v[40:41]
	v_pk_add_f32 v[130:131], v[130:131], v[42:43]
	global_store_dwordx4 v141, v[128:131], s[92:93]
	v_cvt_pk_bf16_f32 v40, v128, v129
	v_cvt_pk_bf16_f32 v41, v130, v131
	v_lshrrev_b32_e32 v42, 1, v141
	v_pk_mul_f32 v[128:129], v[128:129], v[128:129]
	v_pk_mul_f32 v[130:131], v[130:131], v[130:131]
	global_store_dwordx2 v42, v[40:41], s[20:21]
	v_add_f32_e32 v128, v128, v129
	v_add_f32_e32 v130, v130, v131
	v_add_f32_e32 v149, v128, v130
	v_add_f32_dpp v142, v142, v142 quad_perm:[1,0,3,2] row_mask:0xf bank_mask:0xf bound_ctrl:1
	v_add_f32_dpp v143, v143, v143 quad_perm:[1,0,3,2] row_mask:0xf bank_mask:0xf bound_ctrl:1
	v_add_f32_dpp v144, v144, v144 quad_perm:[1,0,3,2] row_mask:0xf bank_mask:0xf bound_ctrl:1
	v_add_f32_dpp v145, v145, v145 quad_perm:[1,0,3,2] row_mask:0xf bank_mask:0xf bound_ctrl:1
	v_add_f32_dpp v146, v146, v146 quad_perm:[1,0,3,2] row_mask:0xf bank_mask:0xf bound_ctrl:1
	v_add_f32_dpp v147, v147, v147 quad_perm:[1,0,3,2] row_mask:0xf bank_mask:0xf bound_ctrl:1
	v_add_f32_dpp v148, v148, v148 quad_perm:[1,0,3,2] row_mask:0xf bank_mask:0xf bound_ctrl:1
	v_add_f32_dpp v149, v149, v149 quad_perm:[1,0,3,2] row_mask:0xf bank_mask:0xf bound_ctrl:1
	v_add_f32_dpp v142, v142, v142 quad_perm:[2,3,0,1] row_mask:0xf bank_mask:0xf bound_ctrl:1
	v_add_f32_dpp v143, v143, v143 quad_perm:[2,3,0,1] row_mask:0xf bank_mask:0xf bound_ctrl:1
	v_add_f32_dpp v144, v144, v144 quad_perm:[2,3,0,1] row_mask:0xf bank_mask:0xf bound_ctrl:1
	v_add_f32_dpp v145, v145, v145 quad_perm:[2,3,0,1] row_mask:0xf bank_mask:0xf bound_ctrl:1
	v_add_f32_dpp v146, v146, v146 quad_perm:[2,3,0,1] row_mask:0xf bank_mask:0xf bound_ctrl:1
	v_add_f32_dpp v147, v147, v147 quad_perm:[2,3,0,1] row_mask:0xf bank_mask:0xf bound_ctrl:1
	v_add_f32_dpp v148, v148, v148 quad_perm:[2,3,0,1] row_mask:0xf bank_mask:0xf bound_ctrl:1
	v_add_f32_dpp v149, v149, v149 quad_perm:[2,3,0,1] row_mask:0xf bank_mask:0xf bound_ctrl:1
	v_add_f32_dpp v142, v142, v142 row_half_mirror row_mask:0xf bank_mask:0xf bound_ctrl:1
	v_add_f32_dpp v143, v143, v143 row_half_mirror row_mask:0xf bank_mask:0xf bound_ctrl:1
	v_add_f32_dpp v144, v144, v144 row_half_mirror row_mask:0xf bank_mask:0xf bound_ctrl:1
	v_add_f32_dpp v145, v145, v145 row_half_mirror row_mask:0xf bank_mask:0xf bound_ctrl:1
	v_add_f32_dpp v146, v146, v146 row_half_mirror row_mask:0xf bank_mask:0xf bound_ctrl:1
	v_add_f32_dpp v147, v147, v147 row_half_mirror row_mask:0xf bank_mask:0xf bound_ctrl:1
	v_add_f32_dpp v148, v148, v148 row_half_mirror row_mask:0xf bank_mask:0xf bound_ctrl:1
	v_add_f32_dpp v149, v149, v149 row_half_mirror row_mask:0xf bank_mask:0xf bound_ctrl:1
	v_add_f32_dpp v142, v142, v142 row_mirror row_mask:0xf bank_mask:0xf bound_ctrl:1
	v_add_f32_dpp v143, v143, v143 row_mirror row_mask:0xf bank_mask:0xf bound_ctrl:1
	v_add_f32_dpp v144, v144, v144 row_mirror row_mask:0xf bank_mask:0xf bound_ctrl:1
	v_add_f32_dpp v145, v145, v145 row_mirror row_mask:0xf bank_mask:0xf bound_ctrl:1
	v_add_f32_dpp v146, v146, v146 row_mirror row_mask:0xf bank_mask:0xf bound_ctrl:1
	v_add_f32_dpp v147, v147, v147 row_mirror row_mask:0xf bank_mask:0xf bound_ctrl:1
	v_add_f32_dpp v148, v148, v148 row_mirror row_mask:0xf bank_mask:0xf bound_ctrl:1
	v_add_f32_dpp v149, v149, v149 row_mirror row_mask:0xf bank_mask:0xf bound_ctrl:1
	ds_bpermute_b32 v12, v182, v142
	ds_bpermute_b32 v16, v182, v143
	ds_bpermute_b32 v20, v182, v144
	ds_bpermute_b32 v24, v182, v145
	ds_bpermute_b32 v28, v182, v146
	ds_bpermute_b32 v32, v182, v147
	ds_bpermute_b32 v36, v182, v148
	ds_bpermute_b32 v40, v182, v149
	s_waitcnt lgkmcnt(0)
	v_add_f32_e32 v142, v142, v12
	v_add_f32_e32 v143, v143, v16
	v_add_f32_e32 v144, v144, v20
	v_add_f32_e32 v145, v145, v24
	v_add_f32_e32 v146, v146, v28
	v_add_f32_e32 v147, v147, v32
	v_add_f32_e32 v148, v148, v36
	v_add_f32_e32 v149, v149, v40
	v_add_u32_e32 v13, 0x200, v99
	v_add_u32_e32 v17, 0x240, v99
	v_add_u32_e32 v21, 0x280, v99
	v_add_u32_e32 v25, 0x2c0, v99
	v_add_u32_e32 v29, 0x300, v99
	v_add_u32_e32 v33, 0x340, v99
	v_add_u32_e32 v37, 0x380, v99
	v_add_u32_e32 v41, 0x3c0, v99
	s_mov_b64 exec, s[0:1]
	global_atomic_add_f32 v13, v142, s[50:51]
	global_atomic_add_f32 v17, v143, s[50:51]
	global_atomic_add_f32 v21, v144, s[50:51]
	global_atomic_add_f32 v25, v145, s[50:51]
	global_atomic_add_f32 v29, v146, s[50:51]
	global_atomic_add_f32 v33, v147, s[50:51]
	global_atomic_add_f32 v37, v148, s[50:51]
	global_atomic_add_f32 v41, v149, s[50:51]
	s_mov_b64 exec, -1
	s_branch .LBB0_158
.Lcepi_last:
	ds_read_b128 v[12:15], v61 offset:0
	v_mov_b32_e32 v134, v98
	global_load_dwordx4 v[100:103], v134, s[92:93]
	ds_read_b128 v[16:19], v61 offset:8448
	v_add_u32_e32 v135, 0x10000, v98
	global_load_dwordx4 v[104:107], v135, s[92:93]
	ds_read_b128 v[20:23], v61 offset:16896
	v_add_u32_e32 v136, 0x20000, v98
	global_load_dwordx4 v[108:111], v136, s[92:93]
	ds_read_b128 v[24:27], v61 offset:25344
	v_add_u32_e32 v137, 0x30000, v98
	global_load_dwordx4 v[112:115], v137, s[92:93]
	ds_read_b128 v[28:31], v61 offset:33792
	v_add_u32_e32 v138, 0x40000, v98
	global_load_dwordx4 v[116:119], v138, s[92:93]
	ds_read_b128 v[32:35], v61 offset:42240
	v_add_u32_e32 v139, 0x50000, v98
	global_load_dwordx4 v[120:123], v139, s[92:93]
	ds_read_b128 v[36:39], v61 offset:50688
	v_add_u32_e32 v140, 0x60000, v98
	global_load_dwordx4 v[124:127], v140, s[92:93]
	ds_read_b128 v[40:43], v61 offset:59136
	v_add_u32_e32 v141, 0x70000, v98
	global_load_dwordx4 v[128:131], v141, s[92:93]
	s_waitcnt vmcnt(7) lgkmcnt(7)
	v_pk_add_f32 v[100:101], v[100:101], v[12:13]
	v_pk_add_f32 v[102:103], v[102:103], v[14:15]
	global_store_dwordx4 v134, v[100:103], s[92:93]
	s_waitcnt vmcnt(7) lgkmcnt(6)
	v_pk_add_f32 v[104:105], v[104:105], v[16:17]
	v_pk_add_f32 v[106:107], v[106:107], v[18:19]
	global_store_dwordx4 v135, v[104:107], s[92:93]
	s_waitcnt vmcnt(7) lgkmcnt(5)
	v_pk_add_f32 v[108:109], v[108:109], v[20:21]
	v_pk_add_f32 v[110:111], v[110:111], v[22:23]
	global_store_dwordx4 v136, v[108:111], s[92:93]
	s_waitcnt vmcnt(7) lgkmcnt(4)
	v_pk_add_f32 v[112:113], v[112:113], v[24:25]
	v_pk_add_f32 v[114:115], v[114:115], v[26:27]
	global_store_dwordx4 v137, v[112:115], s[92:93]
	s_waitcnt vmcnt(7) lgkmcnt(3)
	v_pk_add_f32 v[116:117], v[116:117], v[28:29]
	v_pk_add_f32 v[118:119], v[118:119], v[30:31]
	global_store_dwordx4 v138, v[116:119], s[92:93]
	s_waitcnt vmcnt(7) lgkmcnt(2)
	v_pk_add_f32 v[120:121], v[120:121], v[32:33]
	v_pk_add_f32 v[122:123], v[122:123], v[34:35]
	global_store_dwordx4 v139, v[120:123], s[92:93]
	s_waitcnt vmcnt(7) lgkmcnt(1)
	v_pk_add_f32 v[124:125], v[124:125], v[36:37]
	v_pk_add_f32 v[126:127], v[126:127], v[38:39]
	global_store_dwordx4 v140, v[124:127], s[92:93]
	s_waitcnt vmcnt(7) lgkmcnt(0)
	v_pk_add_f32 v[128:129], v[128:129], v[40:41]
	v_pk_add_f32 v[130:131], v[130:131], v[42:43]
	global_store_dwordx4 v141, v[128:131], s[92:93]
	ds_read_b128 v[12:15], v62 offset:0
	v_add_u32_e32 v134, 0x80000, v98
	global_load_dwordx4 v[100:103], v134, s[92:93]
	ds_read_b128 v[16:19], v62 offset:8448
	v_add_u32_e32 v135, 0x90000, v98
	global_load_dwordx4 v[104:107], v135, s[92:93]
	ds_read_b128 v[20:23], v62 offset:16896
	v_add_u32_e32 v136, 0xa0000, v98
	global_load_dwordx4 v[108:111], v136, s[92:93]
	ds_read_b128 v[24:27], v62 offset:25344
	v_add_u32_e32 v137, 0xb0000, v98
	global_load_dwordx4 v[112:115], v137, s[92:93]
	ds_read_b128 v[28:31], v62 offset:33792
	v_add_u32_e32 v138, 0xc0000, v98
	global_load_dwordx4 v[116:119], v138, s[92:93]
	ds_read_b128 v[32:35], v62 offset:42240
	v_add_u32_e32 v139, 0xd0000, v98
	global_load_dwordx4 v[120:123], v139, s[92:93]
	ds_read_b128 v[36:39], v62 offset:50688
	v_add_u32_e32 v140, 0xe0000, v98
	global_load_dwordx4 v[124:127], v140, s[92:93]
	ds_read_b128 v[40:43], v62 offset:59136
	v_add_u32_e32 v141, 0xf0000, v98
	global_load_dwordx4 v[128:131], v141, s[92:93]
	s_waitcnt vmcnt(7) lgkmcnt(7)
	v_pk_add_f32 v[100:101], v[100:101], v[12:13]
	v_pk_add_f32 v[102:103], v[102:103], v[14:15]
	global_store_dwordx4 v134, v[100:103], s[92:93]
	s_waitcnt vmcnt(7) lgkmcnt(6)
	v_pk_add_f32 v[104:105], v[104:105], v[16:17]
	v_pk_add_f32 v[106:107], v[106:107], v[18:19]
	global_store_dwordx4 v135, v[104:107], s[92:93]
	s_waitcnt vmcnt(7) lgkmcnt(5)
	v_pk_add_f32 v[108:109], v[108:109], v[20:21]
	v_pk_add_f32 v[110:111], v[110:111], v[22:23]
	global_store_dwordx4 v136, v[108:111], s[92:93]
	s_waitcnt vmcnt(7) lgkmcnt(4)
	v_pk_add_f32 v[112:113], v[112:113], v[24:25]
	v_pk_add_f32 v[114:115], v[114:115], v[26:27]
	global_store_dwordx4 v137, v[112:115], s[92:93]
	s_waitcnt vmcnt(7) lgkmcnt(3)
	v_pk_add_f32 v[116:117], v[116:117], v[28:29]
	v_pk_add_f32 v[118:119], v[118:119], v[30:31]
	global_store_dwordx4 v138, v[116:119], s[92:93]
	s_waitcnt vmcnt(7) lgkmcnt(2)
	v_pk_add_f32 v[120:121], v[120:121], v[32:33]
	v_pk_add_f32 v[122:123], v[122:123], v[34:35]
	global_store_dwordx4 v139, v[120:123], s[92:93]
	s_waitcnt vmcnt(7) lgkmcnt(1)
	v_pk_add_f32 v[124:125], v[124:125], v[36:37]
	v_pk_add_f32 v[126:127], v[126:127], v[38:39]
	global_store_dwordx4 v140, v[124:127], s[92:93]
	s_waitcnt vmcnt(7) lgkmcnt(0)
	v_pk_add_f32 v[128:129], v[128:129], v[40:41]
	v_pk_add_f32 v[130:131], v[130:131], v[42:43]
	global_store_dwordx4 v141, v[128:131], s[92:93]
	s_branch .LBB0_158

.LBB0_281:
	s_and_b64 vcc, exec, s[0:1]
	s_cbranch_vccz .LBB0_316
	v_readlane_b32 s0, v214, 25
	v_readlane_b32 s1, v214, 26
	s_mov_b64 s[34:35], s[54:55]
	v_mov_b32_e32 v4, v133
	s_andn2_b64 vcc, exec, s[0:1]
	s_cbranch_vccnz .LBB0_287
	v_readlane_b32 s20, v216, 3
	s_cmpk_lg_i32 s20, 0x100
	s_cbranch_scc1 .Lb2d_orig
	v_readlane_b32 s56, v213, 52
	v_readlane_b32 s57, v213, 53
	v_lshrrev_b32_e32 v124, 3, v133
	v_and_b32_e32 v125, 7, v133
	v_lshlrev_b32_e32 v126, 5, v125
	v_lshl_add_u32 v127, v124, 8, v126
	v_lshlrev_b32_e32 v128, 2, v124
	v_readlane_b32 s2, v216, 0
	s_mov_b32 s58, 0x01010101
	s_mov_b32 s59, 0x01010101
	s_add_i32 s20, s2, 0
	s_lshr_b32 s21, s20, 3
	s_and_b32 s22, s20, 7
	s_lshl_b32 s23, s76, 7
	s_add_i32 s23, s23, s21
	s_lshl_b32 s23, s23, 3
	s_add_i32 s23, s23, s22
	s_lshl_b32 s23, s23, 14
	v_add_u32_e32 v129, s23, v127
	global_load_dwordx4 v[12:15], v129, s[56:57]
	global_load_dwordx4 v[16:19], v129, s[56:57] offset:16
	s_addk_i32 s21, 0x4000
	s_lshl_b32 s23, s21, 3
	s_add_i32 s23, s23, s22
	s_mul_i32 s23, s23, 0x600
	s_add_u32 s23, s23, 0xcf90000
	v_add_u32_e32 v130, s23, v126
	global_load_dwordx4 v[20:23], v130, s[94:95] offset:0
	global_load_dwordx4 v[24:27], v130, s[94:95] offset:16
	global_load_dwordx4 v[28:31], v130, s[94:95] offset:256
	global_load_dwordx4 v[32:35], v130, s[94:95] offset:272
	global_load_dwordx4 v[36:39], v130, s[94:95] offset:512
	global_load_dwordx4 v[40:43], v130, s[94:95] offset:528
	global_load_dwordx4 v[44:47], v130, s[94:95] offset:768
	global_load_dwordx4 v[48:51], v130, s[94:95] offset:784
	global_load_dwordx4 v[52:55], v130, s[94:95] offset:1024
	global_load_dwordx4 v[56:59], v130, s[94:95] offset:1040
	v_add_u32_e32 v131, s23, v128
	global_load_dword v60, v131, s[94:95] offset:1280
	s_add_i32 s20, s2, 256
	s_lshr_b32 s21, s20, 3
	s_and_b32 s22, s20, 7
	s_lshl_b32 s23, s76, 7
	s_add_i32 s23, s23, s21
	s_lshl_b32 s23, s23, 3
	s_add_i32 s23, s23, s22
	s_lshl_b32 s23, s23, 14
	v_add_u32_e32 v10, s23, v127
	global_load_dwordx4 v[68:71], v10, s[56:57]
	global_load_dwordx4 v[72:75], v10, s[56:57] offset:16
	s_addk_i32 s21, 0x4000
	s_lshl_b32 s23, s21, 3
	s_add_i32 s23, s23, s22
	s_mul_i32 s23, s23, 0x600
	s_add_u32 s23, s23, 0xcf90000
	v_add_u32_e32 v11, s23, v126
	global_load_dwordx4 v[76:79], v11, s[94:95] offset:0
	global_load_dwordx4 v[80:83], v11, s[94:95] offset:16
	global_load_dwordx4 v[84:87], v11, s[94:95] offset:256
	global_load_dwordx4 v[88:91], v11, s[94:95] offset:272
	global_load_dwordx4 v[92:95], v11, s[94:95] offset:512
	global_load_dwordx4 v[96:99], v11, s[94:95] offset:528
	global_load_dwordx4 v[100:103], v11, s[94:95] offset:768
	global_load_dwordx4 v[104:107], v11, s[94:95] offset:784
	global_load_dwordx4 v[108:111], v11, s[94:95] offset:1024
	global_load_dwordx4 v[112:115], v11, s[94:95] offset:1040
	v_add_u32_e32 v9, s23, v128
	global_load_dword v116, v9, s[94:95] offset:1280
	s_waitcnt vmcnt(13)
	v_pk_mul_f32 v[120:121], v[12:13], v[28:29]
	v_pk_mul_f32 v[122:123], v[12:13], v[52:53]
	v_pk_fma_f32 v[120:121], v[14:15], v[30:31], v[120:121]
	v_pk_fma_f32 v[122:123], v[14:15], v[54:55], v[122:123]
	v_pk_fma_f32 v[120:121], v[16:17], v[32:33], v[120:121]
	v_pk_fma_f32 v[122:123], v[16:17], v[56:57], v[122:123]
	v_pk_fma_f32 v[120:121], v[18:19], v[34:35], v[120:121]
	v_pk_fma_f32 v[122:123], v[18:19], v[58:59], v[122:123]
	v_add_f32_e32 v120, v120, v121
	v_add_f32_e32 v122, v122, v123
	v_pk_mul_f32 v[12:13], v[12:13], v[20:21]
	v_add_f32_dpp v120, v120, v120 quad_perm:[1,0,3,2] row_mask:0xf bank_mask:0xf bound_ctrl:1
	v_add_f32_dpp v122, v122, v122 quad_perm:[1,0,3,2] row_mask:0xf bank_mask:0xf bound_ctrl:1
	v_pk_mul_f32 v[14:15], v[14:15], v[22:23]
	v_pk_mul_f32 v[16:17], v[16:17], v[24:25]
	v_add_f32_dpp v120, v120, v120 quad_perm:[2,3,0,1] row_mask:0xf bank_mask:0xf bound_ctrl:1
	v_add_f32_dpp v122, v122, v122 quad_perm:[2,3,0,1] row_mask:0xf bank_mask:0xf bound_ctrl:1
	v_pk_mul_f32 v[18:19], v[18:19], v[26:27]
	v_pk_fma_f32 v[12:13], v[60:61], v[44:45], v[12:13] op_sel_hi:[0,1,1]
	v_add_f32_dpp v120, v120, v120 row_half_mirror row_mask:0xf bank_mask:0xf bound_ctrl:1
	v_add_f32_dpp v122, v122, v122 row_half_mirror row_mask:0xf bank_mask:0xf bound_ctrl:1
	v_pk_fma_f32 v[14:15], v[60:61], v[46:47], v[14:15] op_sel_hi:[0,1,1]
	v_pk_fma_f32 v[16:17], v[60:61], v[48:49], v[16:17] op_sel_hi:[0,1,1]
	v_pk_fma_f32 v[18:19], v[60:61], v[50:51], v[18:19] op_sel_hi:[0,1,1]
	v_pk_fma_f32 v[12:13], v[120:121], v[36:37], v[12:13] op_sel_hi:[0,1,1] neg_lo:[1,0,0] neg_hi:[1,0,0]
	v_pk_fma_f32 v[14:15], v[120:121], v[38:39], v[14:15] op_sel_hi:[0,1,1] neg_lo:[1,0,0] neg_hi:[1,0,0]
	v_pk_fma_f32 v[16:17], v[120:121], v[40:41], v[16:17] op_sel_hi:[0,1,1] neg_lo:[1,0,0] neg_hi:[1,0,0]
	v_pk_fma_f32 v[18:19], v[120:121], v[42:43], v[18:19] op_sel_hi:[0,1,1] neg_lo:[1,0,0] neg_hi:[1,0,0]
	v_add_u32_e32 v129, 0x5fec000, v129
	global_store_dwordx4 v129, v[12:15], s[92:93]
	global_store_dwordx4 v129, v[16:19], s[92:93] offset:16
	s_add_i32 s20, s2, 0
	s_lshr_b32 s21, s20, 3
	s_and_b32 s22, s20, 7
	s_addk_i32 s21, 0x4000
	s_lshl_b32 s21, s21, 11
	s_lshl_b32 s22, s22, 8
	s_add_i32 s21, s21, s22
	s_add_u32 s21, s21, 0x19314000
	v_add_u32_e32 v131, s21, v128
	s_mov_b64 exec, s[58:59]
	global_store_dword v131, v122, s[94:95]
	s_mov_b64 exec, -1
	s_nop 1
	s_add_i32 s20, s2, 512
	s_lshr_b32 s21, s20, 3
	s_and_b32 s22, s20, 7
	s_lshl_b32 s23, s76, 7
	s_add_i32 s23, s23, s21
	s_lshl_b32 s23, s23, 3
	s_add_i32 s23, s23, s22
	s_lshl_b32 s23, s23, 14
	v_add_u32_e32 v129, s23, v127
	global_load_dwordx4 v[12:15], v129, s[56:57]
	global_load_dwordx4 v[16:19], v129, s[56:57] offset:16
	s_addk_i32 s21, 0x4000
	s_lshl_b32 s23, s21, 3
	s_add_i32 s23, s23, s22
	s_mul_i32 s23, s23, 0x600
	s_add_u32 s23, s23, 0xcf90000
	v_add_u32_e32 v130, s23, v126
	global_load_dwordx4 v[20:23], v130, s[94:95] offset:0
	global_load_dwordx4 v[24:27], v130, s[94:95] offset:16
	global_load_dwordx4 v[28:31], v130, s[94:95] offset:256
	global_load_dwordx4 v[32:35], v130, s[94:95] offset:272
	global_load_dwordx4 v[36:39], v130, s[94:95] offset:512
	global_load_dwordx4 v[40:43], v130, s[94:95] offset:528
	global_load_dwordx4 v[44:47], v130, s[94:95] offset:768
	global_load_dwordx4 v[48:51], v130, s[94:95] offset:784
	global_load_dwordx4 v[52:55], v130, s[94:95] offset:1024
	global_load_dwordx4 v[56:59], v130, s[94:95] offset:1040
	v_add_u32_e32 v131, s23, v128
	global_load_dword v60, v131, s[94:95] offset:1280
	s_waitcnt vmcnt(16)
	v_pk_mul_f32 v[120:121], v[68:69], v[84:85]
	v_pk_mul_f32 v[122:123], v[68:69], v[108:109]
	v_pk_fma_f32 v[120:121], v[70:71], v[86:87], v[120:121]
	v_pk_fma_f32 v[122:123], v[70:71], v[110:111], v[122:123]
	v_pk_fma_f32 v[120:121], v[72:73], v[88:89], v[120:121]
	v_pk_fma_f32 v[122:123], v[72:73], v[112:113], v[122:123]
	v_pk_fma_f32 v[120:121], v[74:75], v[90:91], v[120:121]
	v_pk_fma_f32 v[122:123], v[74:75], v[114:115], v[122:123]
	v_add_f32_e32 v120, v120, v121
	v_add_f32_e32 v122, v122, v123
	v_pk_mul_f32 v[68:69], v[68:69], v[76:77]
	v_add_f32_dpp v120, v120, v120 quad_perm:[1,0,3,2] row_mask:0xf bank_mask:0xf bound_ctrl:1
	v_add_f32_dpp v122, v122, v122 quad_perm:[1,0,3,2] row_mask:0xf bank_mask:0xf bound_ctrl:1
	v_pk_mul_f32 v[70:71], v[70:71], v[78:79]
	v_pk_mul_f32 v[72:73], v[72:73], v[80:81]
	v_add_f32_dpp v120, v120, v120 quad_perm:[2,3,0,1] row_mask:0xf bank_mask:0xf bound_ctrl:1
	v_add_f32_dpp v122, v122, v122 quad_perm:[2,3,0,1] row_mask:0xf bank_mask:0xf bound_ctrl:1
	v_pk_mul_f32 v[74:75], v[74:75], v[82:83]
	v_pk_fma_f32 v[68:69], v[116:117], v[100:101], v[68:69] op_sel_hi:[0,1,1]
	v_add_f32_dpp v120, v120, v120 row_half_mirror row_mask:0xf bank_mask:0xf bound_ctrl:1
	v_add_f32_dpp v122, v122, v122 row_half_mirror row_mask:0xf bank_mask:0xf bound_ctrl:1
	v_pk_fma_f32 v[70:71], v[116:117], v[102:103], v[70:71] op_sel_hi:[0,1,1]
	v_pk_fma_f32 v[72:73], v[116:117], v[104:105], v[72:73] op_sel_hi:[0,1,1]
	v_pk_fma_f32 v[74:75], v[116:117], v[106:107], v[74:75] op_sel_hi:[0,1,1]
	v_pk_fma_f32 v[68:69], v[120:121], v[92:93], v[68:69] op_sel_hi:[0,1,1] neg_lo:[1,0,0] neg_hi:[1,0,0]
	v_pk_fma_f32 v[70:71], v[120:121], v[94:95], v[70:71] op_sel_hi:[0,1,1] neg_lo:[1,0,0] neg_hi:[1,0,0]
	v_pk_fma_f32 v[72:73], v[120:121], v[96:97], v[72:73] op_sel_hi:[0,1,1] neg_lo:[1,0,0] neg_hi:[1,0,0]
	v_pk_fma_f32 v[74:75], v[120:121], v[98:99], v[74:75] op_sel_hi:[0,1,1] neg_lo:[1,0,0] neg_hi:[1,0,0]
	v_add_u32_e32 v10, 0x5fec000, v10
	global_store_dwordx4 v10, v[68:71], s[92:93]
	global_store_dwordx4 v10, v[72:75], s[92:93] offset:16
	s_add_i32 s20, s2, 256
	s_lshr_b32 s21, s20, 3
	s_and_b32 s22, s20, 7
	s_addk_i32 s21, 0x4000
	s_lshl_b32 s21, s21, 11
	s_lshl_b32 s22, s22, 8
	s_add_i32 s21, s21, s22
	s_add_u32 s21, s21, 0x19314000
	v_add_u32_e32 v9, s21, v128
	s_mov_b64 exec, s[58:59]
	global_store_dword v9, v122, s[94:95]
	s_mov_b64 exec, -1
	s_nop 1
	s_add_i32 s20, s2, 768
	s_lshr_b32 s21, s20, 3
	s_and_b32 s22, s20, 7
	s_lshl_b32 s23, s76, 7
	s_add_i32 s23, s23, s21
	s_lshl_b32 s23, s23, 3
	s_add_i32 s23, s23, s22
	s_lshl_b32 s23, s23, 14
	v_add_u32_e32 v10, s23, v127
	global_load_dwordx4 v[68:71], v10, s[56:57]
	global_load_dwordx4 v[72:75], v10, s[56:57] offset:16
	s_addk_i32 s21, 0x4000
	s_lshl_b32 s23, s21, 3
	s_add_i32 s23, s23, s22
	s_mul_i32 s23, s23, 0x600
	s_add_u32 s23, s23, 0xcf90000
	v_add_u32_e32 v11, s23, v126
	global_load_dwordx4 v[76:79], v11, s[94:95] offset:0
	global_load_dwordx4 v[80:83], v11, s[94:95] offset:16
	global_load_dwordx4 v[84:87], v11, s[94:95] offset:256
	global_load_dwordx4 v[88:91], v11, s[94:95] offset:272
	global_load_dwordx4 v[92:95], v11, s[94:95] offset:512
	global_load_dwordx4 v[96:99], v11, s[94:95] offset:528
	global_load_dwordx4 v[100:103], v11, s[94:95] offset:768
	global_load_dwordx4 v[104:107], v11, s[94:95] offset:784
	global_load_dwordx4 v[108:111], v11, s[94:95] offset:1024
	global_load_dwordx4 v[112:115], v11, s[94:95] offset:1040
	v_add_u32_e32 v9, s23, v128
	global_load_dword v116, v9, s[94:95] offset:1280
	s_waitcnt vmcnt(16)
	v_pk_mul_f32 v[120:121], v[12:13], v[28:29]
	v_pk_mul_f32 v[122:123], v[12:13], v[52:53]
	v_pk_fma_f32 v[120:121], v[14:15], v[30:31], v[120:121]
	v_pk_fma_f32 v[122:123], v[14:15], v[54:55], v[122:123]
	v_pk_fma_f32 v[120:121], v[16:17], v[32:33], v[120:121]
	v_pk_fma_f32 v[122:123], v[16:17], v[56:57], v[122:123]
	v_pk_fma_f32 v[120:121], v[18:19], v[34:35], v[120:121]
	v_pk_fma_f32 v[122:123], v[18:19], v[58:59], v[122:123]
	v_add_f32_e32 v120, v120, v121
	v_add_f32_e32 v122, v122, v123
	v_pk_mul_f32 v[12:13], v[12:13], v[20:21]
	v_add_f32_dpp v120, v120, v120 quad_perm:[1,0,3,2] row_mask:0xf bank_mask:0xf bound_ctrl:1
	v_add_f32_dpp v122, v122, v122 quad_perm:[1,0,3,2] row_mask:0xf bank_mask:0xf bound_ctrl:1
	v_pk_mul_f32 v[14:15], v[14:15], v[22:23]
	v_pk_mul_f32 v[16:17], v[16:17], v[24:25]
	v_add_f32_dpp v120, v120, v120 quad_perm:[2,3,0,1] row_mask:0xf bank_mask:0xf bound_ctrl:1
	v_add_f32_dpp v122, v122, v122 quad_perm:[2,3,0,1] row_mask:0xf bank_mask:0xf bound_ctrl:1
	v_pk_mul_f32 v[18:19], v[18:19], v[26:27]
	v_pk_fma_f32 v[12:13], v[60:61], v[44:45], v[12:13] op_sel_hi:[0,1,1]
	v_add_f32_dpp v120, v120, v120 row_half_mirror row_mask:0xf bank_mask:0xf bound_ctrl:1
	v_add_f32_dpp v122, v122, v122 row_half_mirror row_mask:0xf bank_mask:0xf bound_ctrl:1
	v_pk_fma_f32 v[14:15], v[60:61], v[46:47], v[14:15] op_sel_hi:[0,1,1]
	v_pk_fma_f32 v[16:17], v[60:61], v[48:49], v[16:17] op_sel_hi:[0,1,1]
	v_pk_fma_f32 v[18:19], v[60:61], v[50:51], v[18:19] op_sel_hi:[0,1,1]
	v_pk_fma_f32 v[12:13], v[120:121], v[36:37], v[12:13] op_sel_hi:[0,1,1] neg_lo:[1,0,0] neg_hi:[1,0,0]
	v_pk_fma_f32 v[14:15], v[120:121], v[38:39], v[14:15] op_sel_hi:[0,1,1] neg_lo:[1,0,0] neg_hi:[1,0,0]
	v_pk_fma_f32 v[16:17], v[120:121], v[40:41], v[16:17] op_sel_hi:[0,1,1] neg_lo:[1,0,0] neg_hi:[1,0,0]
	v_pk_fma_f32 v[18:19], v[120:121], v[42:43], v[18:19] op_sel_hi:[0,1,1] neg_lo:[1,0,0] neg_hi:[1,0,0]
	v_add_u32_e32 v129, 0x5fec000, v129
	global_store_dwordx4 v129, v[12:15], s[92:93]
	global_store_dwordx4 v129, v[16:19], s[92:93] offset:16
	s_add_i32 s20, s2, 512
	s_lshr_b32 s21, s20, 3
	s_and_b32 s22, s20, 7
	s_addk_i32 s21, 0x4000
	s_lshl_b32 s21, s21, 11
	s_lshl_b32 s22, s22, 8
	s_add_i32 s21, s21, s22
	s_add_u32 s21, s21, 0x19314000
	v_add_u32_e32 v131, s21, v128
	s_mov_b64 exec, s[58:59]
	global_store_dword v131, v122, s[94:95]
	s_mov_b64 exec, -1
	s_nop 1
	s_waitcnt vmcnt(3)
	v_pk_mul_f32 v[120:121], v[68:69], v[84:85]
	v_pk_mul_f32 v[122:123], v[68:69], v[108:109]
	v_pk_fma_f32 v[120:121], v[70:71], v[86:87], v[120:121]
	v_pk_fma_f32 v[122:123], v[70:71], v[110:111], v[122:123]
	v_pk_fma_f32 v[120:121], v[72:73], v[88:89], v[120:121]
	v_pk_fma_f32 v[122:123], v[72:73], v[112:113], v[122:123]
	v_pk_fma_f32 v[120:121], v[74:75], v[90:91], v[120:121]
	v_pk_fma_f32 v[122:123], v[74:75], v[114:115], v[122:123]
	v_add_f32_e32 v120, v120, v121
	v_add_f32_e32 v122, v122, v123
	v_pk_mul_f32 v[68:69], v[68:69], v[76:77]
	v_add_f32_dpp v120, v120, v120 quad_perm:[1,0,3,2] row_mask:0xf bank_mask:0xf bound_ctrl:1
	v_add_f32_dpp v122, v122, v122 quad_perm:[1,0,3,2] row_mask:0xf bank_mask:0xf bound_ctrl:1
	v_pk_mul_f32 v[70:71], v[70:71], v[78:79]
	v_pk_mul_f32 v[72:73], v[72:73], v[80:81]
	v_add_f32_dpp v120, v120, v120 quad_perm:[2,3,0,1] row_mask:0xf bank_mask:0xf bound_ctrl:1
	v_add_f32_dpp v122, v122, v122 quad_perm:[2,3,0,1] row_mask:0xf bank_mask:0xf bound_ctrl:1
	v_pk_mul_f32 v[74:75], v[74:75], v[82:83]
	v_pk_fma_f32 v[68:69], v[116:117], v[100:101], v[68:69] op_sel_hi:[0,1,1]
	v_add_f32_dpp v120, v120, v120 row_half_mirror row_mask:0xf bank_mask:0xf bound_ctrl:1
	v_add_f32_dpp v122, v122, v122 row_half_mirror row_mask:0xf bank_mask:0xf bound_ctrl:1
	v_pk_fma_f32 v[70:71], v[116:117], v[102:103], v[70:71] op_sel_hi:[0,1,1]
	v_pk_fma_f32 v[72:73], v[116:117], v[104:105], v[72:73] op_sel_hi:[0,1,1]
	v_pk_fma_f32 v[74:75], v[116:117], v[106:107], v[74:75] op_sel_hi:[0,1,1]
	v_pk_fma_f32 v[68:69], v[120:121], v[92:93], v[68:69] op_sel_hi:[0,1,1] neg_lo:[1,0,0] neg_hi:[1,0,0]
	v_pk_fma_f32 v[70:71], v[120:121], v[94:95], v[70:71] op_sel_hi:[0,1,1] neg_lo:[1,0,0] neg_hi:[1,0,0]
	v_pk_fma_f32 v[72:73], v[120:121], v[96:97], v[72:73] op_sel_hi:[0,1,1] neg_lo:[1,0,0] neg_hi:[1,0,0]
	v_pk_fma_f32 v[74:75], v[120:121], v[98:99], v[74:75] op_sel_hi:[0,1,1] neg_lo:[1,0,0] neg_hi:[1,0,0]
	v_add_u32_e32 v10, 0x5fec000, v10
	global_store_dwordx4 v10, v[68:71], s[92:93]
	global_store_dwordx4 v10, v[72:75], s[92:93] offset:16
	s_add_i32 s20, s2, 768
	s_lshr_b32 s21, s20, 3
	s_and_b32 s22, s20, 7
	s_addk_i32 s21, 0x4000
	s_lshl_b32 s21, s21, 11
	s_lshl_b32 s22, s22, 8
	s_add_i32 s21, s21, s22
	s_add_u32 s21, s21, 0x19314000
	v_add_u32_e32 v9, s21, v128
	s_mov_b64 exec, s[58:59]
	global_store_dword v9, v122, s[94:95]
	s_mov_b64 exec, -1
	s_nop 1
	s_branch .LBB0_287
.Lb2d_orig:
	v_and_b32_e32 v6, 64, v192
	v_xor_b32_e32 v5, 1, v192
	v_add_u32_e32 v7, 64, v6
	v_cmp_lt_i32_e32 vcc, v5, v7
	v_xor_b32_e32 v6, 2, v192
	v_ashrrev_i32_e32 v0, 3, v4
	v_cndmask_b32_e32 v5, v192, v5, vcc
	v_cmp_lt_i32_e32 vcc, v6, v7
	s_waitcnt lgkmcnt(0)
	v_xor_b32_e32 v10, 4, v192
	v_and_b32_e32 v9, 7, v4
	s_waitcnt lgkmcnt(0)
	v_ashrrev_i32_e32 v1, 31, v0
	v_cndmask_b32_e32 v6, v192, v6, vcc
	v_cmp_lt_i32_e32 vcc, v10, v7
	v_lshlrev_b64 v[2:3], 6, v[0:1]
	v_lshlrev_b32_e32 v8, 3, v9
	v_cndmask_b32_e32 v7, v192, v10, vcc
	s_lshl_b64 s[0:1], s[76:77], 10
	v_or_b32_e32 v2, v2, v8
	v_lshlrev_b32_e32 v5, 2, v5
	v_lshlrev_b32_e32 v6, 2, v6
	v_lshlrev_b32_e32 v7, 2, v7
	v_cmp_eq_u32_e32 vcc, 0, v9
	v_lshlrev_b32_e32 v8, 2, v8
	v_readlane_b32 s2, v216, 0
	s_branch .LBB0_285
